# fused GEMM2 LayerNorm epilogue: residual x tile loads in bursts into dead operand registers (was one dependent HBM round trip per row group); top-k compare/select chains interleaved
# baseline (speedup 1.0000x reference)
.LBB0_743:
	s_ashr_i32 s1, s10, 31
	s_lshr_b32 s1, s1, 27
	s_add_i32 s1, s10, s1
	s_ashr_i32 s1, s1, 5
	s_lshl_b32 s0, s11, 5
	s_mul_hi_i32 s6, s1, 0x3000
	s_mulk_i32 s1, 0x3000
	s_add_u32 s27, s90, s1
	s_addc_u32 s28, s91, s6
	s_add_u32 s6, s27, 0x2000
	s_addc_u32 s7, s28, 0
	s_lshl_b32 s1, s8, 8
	v_lshrrev_b32_e32 v130, 1, v178
	s_or_b32 s0, s1, s0
	s_lshl_b32 s26, s10, 8
	v_and_or_b32 v156, v130, 24, s0
	s_add_i32 s0, s26, s44
	v_or_b32_e32 v148, s0, v179
	v_ashrrev_i32_e32 v149, 31, v148
	v_readlane_b32 s40, v241, 52
	v_ashrrev_i32_e32 v157, 31, v156
	v_lshlrev_b64 v[138:139], 12, v[148:149]
	v_readlane_b32 s41, v241, 53
	v_lshlrev_b64 v[158:159], 2, v[156:157]
	v_lshl_add_u64 v[134:135], s[6:7], 0, v[158:159]
	v_lshl_add_u64 v[138:139], s[40:41], 0, v[138:139]
	v_lshl_add_u64 v[146:147], v[138:139], 0, v[158:159]
	s_barrier
	global_load_dwordx4 v[130:133], v[134:135], off offset:16
	s_nop 0
	global_load_dwordx4 v[134:137], v[134:135], off
	s_nop 0
	global_load_dwordx4 v[180:183], v[146:147], off nt
	global_load_dwordx4 v[184:187], v[146:147], off offset:16 nt
	v_or_b32_e32 v150, 16, v148
	v_ashrrev_i32_e32 v151, 31, v150
	v_lshlrev_b64 v[150:151], 12, v[150:151]
	s_mov_b32 s0, 0x3fb504f3
	v_lshl_add_u64 v[150:151], s[40:41], 0, v[150:151]
	v_lshl_add_u64 v[160:161], v[150:151], 0, v[158:159]
	v_or_b32_e32 v154, 0x80, v156
	v_ashrrev_i32_e32 v155, 31, v154
	v_lshl_add_u64 v[254:255], v[154:155], 2, s[6:7]
	global_load_dwordx4 v[246:249], v[254:255], off
	global_load_dwordx4 v[250:253], v[254:255], off offset:16
	s_mov_b64 s[98:99], 0x20000
	v_lshl_add_u64 v[162:163], v[146:147], 0, s[98:99]
	s_mov_b64 s[98:99], 0x30000
	v_lshl_add_u64 v[166:167], v[146:147], 0, s[98:99]
	s_mov_b64 s[98:99], 0x80000
	v_lshl_add_u64 v[168:169], v[146:147], 0, s[98:99]
	s_mov_b64 s[98:99], 0x90000
	v_lshl_add_u64 v[170:171], v[146:147], 0, s[98:99]
	s_mov_b64 s[98:99], 0xa0000
	v_lshl_add_u64 v[176:177], v[146:147], 0, s[98:99]
	s_mov_b64 s[98:99], 0xb0000
	v_lshl_add_u64 v[164:165], v[146:147], 0, s[98:99]
	global_load_dwordx4 v[188:191], v[160:161], off nt
	global_load_dwordx4 v[192:195], v[160:161], off offset:16 nt
	global_load_dwordx4 v[196:199], v[162:163], off nt
	global_load_dwordx4 v[200:203], v[162:163], off offset:16 nt
	global_load_dwordx4 v[204:207], v[166:167], off nt
	global_load_dwordx4 v[208:211], v[166:167], off offset:16 nt
	global_load_dwordx4 v[212:215], v[168:169], off nt
	global_load_dwordx4 v[216:219], v[168:169], off offset:16 nt
	global_load_dwordx4 v[220:223], v[170:171], off nt
	global_load_dwordx4 v[224:227], v[170:171], off offset:16 nt
	global_load_dwordx4 v[228:231], v[176:177], off nt
	global_load_dwordx4 v[232:235], v[176:177], off offset:16 nt
	global_load_dwordx4 v[236:239], v[164:165], off nt
	global_load_dwordx4 v[242:245], v[164:165], off offset:16 nt
	v_readlane_b32 s42, v241, 54
	v_readlane_b32 s43, v241, 55
	v_readlane_b32 s44, v241, 56
	v_readlane_b32 s45, v241, 57
	v_readlane_b32 s46, v241, 58
	v_readlane_b32 s47, v241, 59
	v_readlane_b32 s48, v241, 60
	v_readlane_b32 s49, v241, 61
	v_readlane_b32 s50, v241, 62
	v_readlane_b32 s51, v241, 63
	v_readlane_b32 s52, v240, 0
	v_readlane_b32 s53, v240, 1
	v_readlane_b32 s54, v240, 2
	v_readlane_b32 s55, v240, 3
	s_waitcnt vmcnt(16)
	v_pk_add_f32 v[172:173], v[132:133], 1.0 op_sel_hi:[1,0]
	v_pk_add_f32 v[150:151], v[136:137], 1.0 op_sel_hi:[1,0]
	v_pk_add_f32 v[152:153], v[134:135], 1.0 op_sel_hi:[1,0]
	v_pk_add_f32 v[174:175], v[130:131], 1.0 op_sel_hi:[1,0]
	v_pk_mul_f32 v[130:131], v[182:183], s[0:1] op_sel_hi:[1,0]
	v_pk_mul_f32 v[132:133], v[180:181], s[0:1] op_sel_hi:[1,0]
	v_pk_mul_f32 v[134:135], v[186:187], s[0:1] op_sel_hi:[1,0]
	v_pk_mul_f32 v[136:137], v[184:185], s[0:1] op_sel_hi:[1,0]
	v_pk_fma_f32 v[144:145], v[128:129], v[150:151], v[130:131]
	v_pk_fma_f32 v[142:143], v[126:127], v[152:153], v[132:133]
	v_pk_fma_f32 v[140:141], v[124:125], v[172:173], v[134:135]
	v_pk_fma_f32 v[138:139], v[122:123], v[174:175], v[136:137]
	v_or_b32_e32 v130, 32, v148
	global_load_dwordx4 v[180:183], v[146:147], off offset:512 nt
	global_load_dwordx4 v[184:187], v[146:147], off offset:528 nt
	v_ashrrev_i32_e32 v131, 31, v130
	v_lshlrev_b64 v[130:131], 12, v[130:131]
	v_lshl_add_u64 v[130:131], s[40:41], 0, v[130:131]
	v_lshl_add_u64 v[162:163], v[130:131], 0, v[158:159]
	s_waitcnt vmcnt(15)
	v_pk_mul_f32 v[124:125], v[190:191], s[0:1] op_sel_hi:[1,0]
	v_pk_mul_f32 v[122:123], v[188:189], s[0:1] op_sel_hi:[1,0]
	s_waitcnt vmcnt(14)
	v_pk_mul_f32 v[128:129], v[194:195], s[0:1] op_sel_hi:[1,0]
	v_pk_mul_f32 v[126:127], v[192:193], s[0:1] op_sel_hi:[1,0]
	v_pk_fma_f32 v[136:137], v[116:117], v[150:151], v[124:125]
	v_pk_fma_f32 v[134:135], v[114:115], v[152:153], v[122:123]
	v_pk_fma_f32 v[128:129], v[108:109], v[172:173], v[128:129]
	v_pk_fma_f32 v[126:127], v[106:107], v[174:175], v[126:127]
	v_or_b32_e32 v122, 48, v148
	global_load_dwordx4 v[188:191], v[160:161], off offset:512 nt
	global_load_dwordx4 v[192:195], v[160:161], off offset:528 nt
	v_ashrrev_i32_e32 v123, 31, v122
	v_lshlrev_b64 v[122:123], 12, v[122:123]
	v_lshl_add_u64 v[122:123], s[40:41], 0, v[122:123]
	v_lshl_add_u64 v[166:167], v[122:123], 0, v[158:159]
	s_waitcnt vmcnt(15)
	v_pk_mul_f32 v[108:109], v[198:199], s[0:1] op_sel_hi:[1,0]
	v_pk_mul_f32 v[106:107], v[196:197], s[0:1] op_sel_hi:[1,0]
	s_waitcnt vmcnt(14)
	v_pk_mul_f32 v[116:117], v[202:203], s[0:1] op_sel_hi:[1,0]
	v_pk_mul_f32 v[114:115], v[200:201], s[0:1] op_sel_hi:[1,0]
	v_pk_fma_f32 v[132:133], v[104:105], v[150:151], v[108:109]
	v_pk_fma_f32 v[130:131], v[102:103], v[152:153], v[106:107]
	v_pk_fma_f32 v[124:125], v[100:101], v[172:173], v[116:117]
	v_pk_fma_f32 v[122:123], v[98:99], v[174:175], v[114:115]
	v_add_u32_e32 v106, 0x80, v148
	global_load_dwordx4 v[196:199], v[162:163], off offset:512 nt
	global_load_dwordx4 v[200:203], v[162:163], off offset:528 nt
	v_ashrrev_i32_e32 v107, 31, v106
	v_lshlrev_b64 v[106:107], 12, v[106:107]
	v_lshl_add_u64 v[106:107], s[40:41], 0, v[106:107]
	v_lshl_add_u64 v[168:169], v[106:107], 0, v[158:159]
	s_waitcnt vmcnt(15)
	v_pk_mul_f32 v[100:101], v[206:207], s[0:1] op_sel_hi:[1,0]
	v_pk_mul_f32 v[98:99], v[204:205], s[0:1] op_sel_hi:[1,0]
	s_waitcnt vmcnt(14)
	v_pk_mul_f32 v[104:105], v[210:211], s[0:1] op_sel_hi:[1,0]
	v_pk_mul_f32 v[102:103], v[208:209], s[0:1] op_sel_hi:[1,0]
	v_pk_fma_f32 v[116:117], v[96:97], v[150:151], v[100:101]
	v_pk_fma_f32 v[114:115], v[94:95], v[152:153], v[98:99]
	v_pk_fma_f32 v[108:109], v[88:89], v[172:173], v[104:105]
	v_pk_fma_f32 v[106:107], v[86:87], v[174:175], v[102:103]
	v_add_u32_e32 v98, 0x90, v148
	global_load_dwordx4 v[204:207], v[166:167], off offset:512 nt
	global_load_dwordx4 v[208:211], v[166:167], off offset:528 nt
	v_ashrrev_i32_e32 v99, 31, v98
	v_lshlrev_b64 v[98:99], 12, v[98:99]
	v_lshl_add_u64 v[98:99], s[40:41], 0, v[98:99]
	v_lshl_add_u64 v[170:171], v[98:99], 0, v[158:159]
	s_waitcnt vmcnt(15)
	v_pk_mul_f32 v[88:89], v[214:215], s[0:1] op_sel_hi:[1,0]
	v_pk_mul_f32 v[86:87], v[212:213], s[0:1] op_sel_hi:[1,0]
	s_waitcnt vmcnt(14)
	v_pk_mul_f32 v[96:97], v[218:219], s[0:1] op_sel_hi:[1,0]
	v_pk_mul_f32 v[94:95], v[216:217], s[0:1] op_sel_hi:[1,0]
	v_pk_fma_f32 v[104:105], v[80:81], v[150:151], v[88:89]
	v_pk_fma_f32 v[102:103], v[78:79], v[152:153], v[86:87]
	v_pk_fma_f32 v[100:101], v[76:77], v[172:173], v[96:97]
	v_pk_fma_f32 v[98:99], v[74:75], v[174:175], v[94:95]
	v_add_u32_e32 v86, 0xa0, v148
	global_load_dwordx4 v[212:215], v[168:169], off offset:512 nt
	global_load_dwordx4 v[216:219], v[168:169], off offset:528 nt
	v_ashrrev_i32_e32 v87, 31, v86
	v_lshlrev_b64 v[86:87], 12, v[86:87]
	v_lshl_add_u64 v[86:87], s[40:41], 0, v[86:87]
	v_lshl_add_u64 v[176:177], v[86:87], 0, v[158:159]
	s_waitcnt vmcnt(15)
	v_pk_mul_f32 v[76:77], v[222:223], s[0:1] op_sel_hi:[1,0]
	v_pk_mul_f32 v[74:75], v[220:221], s[0:1] op_sel_hi:[1,0]
	s_waitcnt vmcnt(14)
	v_pk_mul_f32 v[80:81], v[226:227], s[0:1] op_sel_hi:[1,0]
	v_pk_mul_f32 v[78:79], v[224:225], s[0:1] op_sel_hi:[1,0]
	v_pk_fma_f32 v[96:97], v[72:73], v[150:151], v[76:77]
	v_pk_fma_f32 v[94:95], v[70:71], v[152:153], v[74:75]
	v_pk_fma_f32 v[88:89], v[68:69], v[172:173], v[80:81]
	v_pk_fma_f32 v[86:87], v[66:67], v[174:175], v[78:79]
	v_add_u32_e32 v74, 0xb0, v148
	global_load_dwordx4 v[220:223], v[170:171], off offset:512 nt
	global_load_dwordx4 v[224:227], v[170:171], off offset:528 nt
	v_ashrrev_i32_e32 v75, 31, v74
	v_lshlrev_b64 v[74:75], 12, v[74:75]
	v_lshl_add_u64 v[74:75], s[40:41], 0, v[74:75]
	v_lshl_add_u64 v[164:165], v[74:75], 0, v[158:159]
	v_lshl_add_u64 v[148:149], v[154:155], 2, s[6:7]
	s_waitcnt vmcnt(15)
	v_pk_mul_f32 v[68:69], v[230:231], s[0:1] op_sel_hi:[1,0]
	v_pk_mul_f32 v[66:67], v[228:229], s[0:1] op_sel_hi:[1,0]
	s_waitcnt vmcnt(14)
	v_pk_mul_f32 v[72:73], v[234:235], s[0:1] op_sel_hi:[1,0]
	v_pk_mul_f32 v[70:71], v[232:233], s[0:1] op_sel_hi:[1,0]
	v_pk_fma_f32 v[80:81], v[64:65], v[150:151], v[68:69]
	v_pk_fma_f32 v[78:79], v[62:63], v[152:153], v[66:67]
	v_pk_fma_f32 v[76:77], v[60:61], v[172:173], v[72:73]
	v_pk_fma_f32 v[74:75], v[58:59], v[174:175], v[70:71]
	s_nop 0
	global_load_dwordx4 v[228:231], v[176:177], off offset:512 nt
	global_load_dwordx4 v[232:235], v[176:177], off offset:528 nt
	s_waitcnt vmcnt(15)
	v_pk_mul_f32 v[60:61], v[238:239], s[0:1] op_sel_hi:[1,0]
	v_pk_mul_f32 v[58:59], v[236:237], s[0:1] op_sel_hi:[1,0]
	s_waitcnt vmcnt(14)
	v_pk_mul_f32 v[64:65], v[244:245], s[0:1] op_sel_hi:[1,0]
	v_pk_mul_f32 v[62:63], v[242:243], s[0:1] op_sel_hi:[1,0]
	v_pk_fma_f32 v[72:73], v[56:57], v[150:151], v[60:61]
	v_pk_fma_f32 v[70:71], v[54:55], v[152:153], v[58:59]
	v_pk_fma_f32 v[68:69], v[52:53], v[172:173], v[64:65]
	v_pk_fma_f32 v[66:67], v[50:51], v[174:175], v[62:63]
	s_nop 0
	s_waitcnt vmcnt(13)
	v_pk_add_f32 v[146:147], v[248:249], 1.0 op_sel_hi:[1,0]
	v_pk_add_f32 v[148:149], v[246:247], 1.0 op_sel_hi:[1,0]
	s_waitcnt vmcnt(13)
	v_pk_add_f32 v[150:151], v[252:253], 1.0 op_sel_hi:[1,0]
	v_pk_add_f32 v[152:153], v[250:251], 1.0 op_sel_hi:[1,0]
	s_waitcnt vmcnt(13)
	v_pk_mul_f32 v[50:51], v[182:183], s[0:1] op_sel_hi:[1,0]
	v_pk_mul_f32 v[52:53], v[180:181], s[0:1] op_sel_hi:[1,0]
	s_waitcnt vmcnt(12)
	v_pk_mul_f32 v[54:55], v[186:187], s[0:1] op_sel_hi:[1,0]
	v_pk_mul_f32 v[56:57], v[184:185], s[0:1] op_sel_hi:[1,0]
	v_pk_fma_f32 v[64:65], v[120:121], v[146:147], v[50:51]
	v_pk_fma_f32 v[62:63], v[118:119], v[148:149], v[52:53]
	v_pk_fma_f32 v[60:61], v[112:113], v[150:151], v[54:55]
	v_pk_fma_f32 v[58:59], v[110:111], v[152:153], v[56:57]
	s_nop 0
	v_mov_b32_e32 v160, v138
	v_mov_b32_e32 v161, v141
	s_waitcnt vmcnt(11)
	v_pk_mul_f32 v[52:53], v[190:191], s[0:1] op_sel_hi:[1,0]
	v_pk_mul_f32 v[50:51], v[188:189], s[0:1] op_sel_hi:[1,0]
	s_waitcnt vmcnt(10)
	v_pk_mul_f32 v[110:111], v[194:195], s[0:1] op_sel_hi:[1,0]
	v_pk_mul_f32 v[112:113], v[192:193], s[0:1] op_sel_hi:[1,0]
	v_pk_fma_f32 v[56:57], v[92:93], v[146:147], v[52:53]
	v_pk_fma_f32 v[54:55], v[90:91], v[148:149], v[50:51]
	v_pk_fma_f32 v[52:53], v[84:85], v[150:151], v[110:111]
	v_pk_fma_f32 v[50:51], v[82:83], v[152:153], v[112:113]
	s_nop 0
	s_waitcnt vmcnt(9)
	v_pk_mul_f32 v[84:85], v[198:199], s[0:1] op_sel_hi:[1,0]
	v_pk_mul_f32 v[82:83], v[196:197], s[0:1] op_sel_hi:[1,0]
	s_waitcnt vmcnt(8)
	v_pk_mul_f32 v[92:93], v[202:203], s[0:1] op_sel_hi:[1,0]
	v_pk_mul_f32 v[90:91], v[200:201], s[0:1] op_sel_hi:[1,0]
	v_pk_fma_f32 v[48:49], v[48:49], v[146:147], v[84:85]
	v_pk_fma_f32 v[46:47], v[46:47], v[148:149], v[82:83]
	v_pk_fma_f32 v[44:45], v[44:45], v[150:151], v[92:93]
	v_pk_fma_f32 v[42:43], v[42:43], v[152:153], v[90:91]
	s_nop 0
	s_waitcnt vmcnt(7)
	v_pk_mul_f32 v[84:85], v[206:207], s[0:1] op_sel_hi:[1,0]
	v_pk_mul_f32 v[82:83], v[204:205], s[0:1] op_sel_hi:[1,0]
	s_waitcnt vmcnt(6)
	v_pk_mul_f32 v[92:93], v[210:211], s[0:1] op_sel_hi:[1,0]
	v_pk_mul_f32 v[90:91], v[208:209], s[0:1] op_sel_hi:[1,0]
	v_pk_fma_f32 v[40:41], v[40:41], v[146:147], v[84:85]
	v_pk_fma_f32 v[38:39], v[38:39], v[148:149], v[82:83]
	v_pk_fma_f32 v[36:37], v[36:37], v[150:151], v[92:93]
	v_pk_fma_f32 v[34:35], v[34:35], v[152:153], v[90:91]
	s_nop 0
	s_waitcnt vmcnt(5)
	v_pk_mul_f32 v[84:85], v[214:215], s[0:1] op_sel_hi:[1,0]
	v_pk_mul_f32 v[82:83], v[212:213], s[0:1] op_sel_hi:[1,0]
	s_waitcnt vmcnt(4)
	v_pk_mul_f32 v[92:93], v[218:219], s[0:1] op_sel_hi:[1,0]
	v_pk_mul_f32 v[90:91], v[216:217], s[0:1] op_sel_hi:[1,0]
	v_pk_fma_f32 v[32:33], v[32:33], v[146:147], v[84:85]
	v_pk_fma_f32 v[30:31], v[30:31], v[148:149], v[82:83]
	v_pk_fma_f32 v[28:29], v[28:29], v[150:151], v[92:93]
	v_pk_fma_f32 v[26:27], v[26:27], v[152:153], v[90:91]
	s_nop 0
	s_waitcnt vmcnt(3)
	v_pk_mul_f32 v[84:85], v[222:223], s[0:1] op_sel_hi:[1,0]
	v_pk_mul_f32 v[82:83], v[220:221], s[0:1] op_sel_hi:[1,0]
	s_waitcnt vmcnt(2)
	v_pk_mul_f32 v[92:93], v[226:227], s[0:1] op_sel_hi:[1,0]
	v_pk_mul_f32 v[90:91], v[224:225], s[0:1] op_sel_hi:[1,0]
	v_pk_fma_f32 v[24:25], v[24:25], v[146:147], v[84:85]
	v_pk_fma_f32 v[22:23], v[22:23], v[148:149], v[82:83]
	v_pk_fma_f32 v[20:21], v[20:21], v[150:151], v[92:93]
	v_pk_fma_f32 v[18:19], v[18:19], v[152:153], v[90:91]
	v_mbcnt_lo_u32_b32 v82, -1, 0
	v_mbcnt_hi_u32_b32 v83, -1, v82
	v_and_b32_e32 v84, 64, v83
	v_add_u32_e32 v162, 64, v84
	v_mov_b32_e32 v84, v143
	v_mov_b32_e32 v85, v144
	v_xor_b32_e32 v82, 16, v83
	v_cmp_lt_i32_e32 vcc, v82, v162
	s_waitcnt vmcnt(1)
	v_pk_mul_f32 v[92:93], v[230:231], s[0:1] op_sel_hi:[1,0]
	v_pk_mul_f32 v[90:91], v[228:229], s[0:1] op_sel_hi:[1,0]
	s_waitcnt vmcnt(0)
	v_pk_mul_f32 v[112:113], v[234:235], s[0:1] op_sel_hi:[1,0]
	v_pk_mul_f32 v[110:111], v[232:233], s[0:1] op_sel_hi:[1,0]
	v_pk_fma_f32 v[16:17], v[16:17], v[146:147], v[92:93]
	v_pk_fma_f32 v[14:15], v[14:15], v[148:149], v[90:91]
	v_pk_fma_f32 v[12:13], v[12:13], v[150:151], v[112:113]
	v_pk_fma_f32 v[10:11], v[10:11], v[152:153], v[110:111]
	v_mov_b32_e32 v90, v142
	global_load_dwordx4 v[110:113], v[164:165], off offset:528
	global_load_dwordx4 v[118:121], v[164:165], off offset:512
	v_mov_b32_e32 v91, v145
	v_mov_b32_e32 v92, v139
	v_mov_b32_e32 v93, v140
	v_pk_add_f32 v[84:85], v[84:85], v[90:91]
	v_pk_add_f32 v[90:91], v[92:93], v[160:161]
	v_add_f32_e32 v92, v84, v85
	v_pk_add_f32 v[84:85], v[90:91], v[90:91] op_sel_hi:[0,1]
	v_add_f32_e32 v91, 0, v92
	v_add_f32_e32 v93, v62, v63
	v_add_f32_e32 v161, v64, v65
	v_mov_b32_e32 v84, v58
	v_mov_b32_e32 v90, v59
	v_mov_b32_e32 v92, v60
	v_mov_b32_e32 v160, v61
	v_pk_add_f32 v[84:85], v[84:85], v[90:91]
	v_pk_add_f32 v[90:91], v[92:93], v[160:161]
	v_cndmask_b32_e32 v82, v83, v82, vcc
	v_pk_add_f32 v[84:85], v[84:85], v[90:91]
	v_lshlrev_b32_e32 v82, 2, v82
	v_add_f32_e32 v84, v84, v85
	ds_bpermute_b32 v85, v82, v84
	v_xor_b32_e32 v90, 32, v83
	v_cmp_lt_i32_e32 vcc, v90, v162
	s_waitcnt lgkmcnt(0)
	v_add_f32_e32 v84, v84, v85
	v_cndmask_b32_e32 v83, v83, v90, vcc
	v_lshlrev_b32_e32 v83, 2, v83
	ds_bpermute_b32 v85, v83, v84
	s_waitcnt lgkmcnt(0)
	v_add_f32_e32 v85, v84, v85
	v_fmamk_f32 v90, v85, 0xbc800000, v145
	v_fmamk_f32 v92, v85, 0xbc800000, v143
	v_fmamk_f32 v160, v85, 0xbc800000, v141
	v_fmamk_f32 v162, v85, 0xbc800000, v139
	v_fmamk_f32 v84, v85, 0xbc800000, v144
	v_fmamk_f32 v91, v85, 0xbc800000, v142
	v_fmamk_f32 v93, v85, 0xbc800000, v140
	v_fmamk_f32 v161, v85, 0xbc800000, v138
	v_fmamk_f32 v164, v85, 0xbc800000, v65
	v_fmamk_f32 v166, v85, 0xbc800000, v63
	v_mul_f32_e32 v92, v92, v92
	v_mul_f32_e32 v90, v90, v90
	v_mul_f32_e32 v162, v162, v162
	v_mul_f32_e32 v160, v160, v160
	v_fmamk_f32 v163, v85, 0xbc800000, v64
	v_fmamk_f32 v165, v85, 0xbc800000, v62
	v_fmamk_f32 v168, v85, 0xbc800000, v61
	v_fmamk_f32 v170, v85, 0xbc800000, v59
	v_mul_f32_e32 v166, v166, v166
	v_mul_f32_e32 v164, v164, v164
	v_fmac_f32_e32 v92, v91, v91
	v_fmac_f32_e32 v90, v84, v84
	v_fmac_f32_e32 v162, v161, v161
	v_fmac_f32_e32 v160, v93, v93
	v_fmamk_f32 v167, v85, 0xbc800000, v60
	v_fmamk_f32 v169, v85, 0xbc800000, v58
	v_mul_f32_e32 v170, v170, v170
	v_mul_f32_e32 v168, v168, v168
	v_fmac_f32_e32 v166, v165, v165
	v_fmac_f32_e32 v164, v163, v163
	v_add_f32_e32 v84, v92, v90
	v_add_f32_e32 v90, v162, v160
	v_fmac_f32_e32 v170, v169, v169
	v_fmac_f32_e32 v168, v167, v167
	v_add_f32_e32 v91, v166, v164
	v_add_f32_e32 v84, v84, v90
	v_add_f32_e32 v92, v170, v168
	v_add_f32_e32 v84, v91, v84
	v_add_f32_e32 v90, v92, v84
	ds_bpermute_b32 v91, v82, v90
	v_and_b32_e32 v84, 63, v178
	v_cmp_gt_u32_e32 vcc, 16, v84
	s_waitcnt lgkmcnt(0)
	v_add_f32_e32 v90, v90, v91
	ds_bpermute_b32 v91, v83, v90
	s_waitcnt vmcnt(0)
	v_pk_mul_f32 v[92:93], v[120:121], s[0:1] op_sel_hi:[1,0]
	v_pk_mul_f32 v[118:119], v[118:119], s[0:1] op_sel_hi:[1,0]
	v_pk_mul_f32 v[112:113], v[112:113], s[0:1] op_sel_hi:[1,0]
	v_pk_mul_f32 v[110:111], v[110:111], s[0:1] op_sel_hi:[1,0]
	v_pk_fma_f32 v[8:9], v[8:9], v[146:147], v[92:93]
	v_pk_fma_f32 v[6:7], v[6:7], v[148:149], v[118:119]
	v_pk_fma_f32 v[4:5], v[4:5], v[150:151], v[112:113]
	v_pk_fma_f32 v[2:3], v[2:3], v[152:153], v[110:111]
	s_lshl_b32 s0, s11, 3
	s_add_i32 s6, s0, 0
	s_and_saveexec_b64 s[0:1], vcc
	s_cbranch_execz .LBB0_745
	s_lshl_b32 s7, s39, 11
	s_add_i32 s7, s6, s7
	v_mul_f32_e32 v92, 0x3c800000, v85
	v_lshl_add_u32 v85, v179, 5, s7
	s_waitcnt lgkmcnt(0)
	v_add_f32_e32 v93, v90, v91
	ds_write_b64 v85, v[92:93]
